# S5: both ntile-0 waves (0 and 4) skip in-projection; ntile-1 waves (1 and 5) compute their tiles
# baseline (speedup 1.0000x reference)
; __device__ __forceinline__ int opaque_tid() { int t = threadIdx.x; asm volatile("" : "+v"(t)); return t; }
; __device__ __forceinline__ void s5_unit(const Args& A, char* lds, int b, int g) {
;     const int tid = opaque_tid(), lane = tid & 63, wave = __builtin_amdgcn_readfirstlane(tid >> 6); const int fr = lane & 15, fq = lane >> 4, r32 = lane & 31, hi = lane >> 5;
;     const bf16* P1 = (const bf16*)(A.ws + WS_BIG); bf16* YD = (bf16*)A.out;
;     const unsigned char* pg = A.ws + WS_S5P + (size_t)g * S5P_STRIDE; const bf16* BbT = (const bf16*)pg; const bf16* Cm = (const bf16*)(pg + 4096); const float* ari = (const float*)(pg + 8192);
;     const int ttile = wave >> 2, ntile = wave & 3;
;     const bf16x8 bfrag = *(const bf16x8*)(BbT + (ntile * 32 + r32) * 16 + 8 * hi);
;     bf16x8 cfrag[4];
; #pragma unroll
;     for (int ks = 0; ks < 4; ++ks) cfrag[ks] = *(const bf16x8*)(Cm + fr * 128 + ks * 32 + 8 * fq);
;     const float ar = ari[lane], ai = ari[64 + lane]; float sr = 0.f, si = 0.f;
;     const float dskip = A.in[I_ODSKIP][g * 16 + fr];
;     const size_t rb0 = (size_t)b * SEQL; const bf16* pU = P1 + (rb0 + ttile * 32 + r32) * LD1 + C1_U + g * 16 + 8 * hi;
;     bf16x8 un = *(const bf16x8*)pU;
.LBB0_1346:
	s_and_b32 s8, s42, 31
	v_mov_b32_e32 v14, v220
	s_lshl_b32 s44, s8, 5
	s_and_b32 s8, s43, 31
	s_ashr_i32 s16, s43, 5
	v_readfirstlane_b32 s20, v14
	s_ashr_i32 s45, s20, 6
	s_and_b32 s98, s45, 3
	s_cmp_eq_u32 s98, 1
	s_cselect_b32 s98, 1, 0
	s_mul_i32 s17, s8, 0x2200
	v_and_b32_e32 v48, 15, v14
	s_add_u32 s18, s4, s17
	s_addc_u32 s19, s5, 0
	v_lshlrev_b32_e32 v2, 8, v48
	v_mov_b32_e32 v3, v41
	v_and_b32_e32 v45, 31, v14
	v_lshl_add_u64 v[2:3], s[18:19], 0, v[2:3]
	v_and_b32_e32 v4, 48, v14
	v_mov_b32_e32 v5, v41
	v_and_b32_e32 v15, 63, v14
	s_and_b32 s21, s45, 3
	v_lshlrev_b32_e32 v0, 5, v45
	v_lshl_add_u64 v[2:3], v[2:3], 0, v[4:5]
	v_bfe_u32 v46, v14, 5, 1
	v_lshl_or_b32 v40, s21, 10, v0
	v_lshl_add_u64 v[6:7], v[2:3], 0, s[10:11]
	v_add_co_u32_e32 v2, vcc, s26, v2
	v_lshlrev_b32_e32 v8, 2, v15
	v_mov_b32_e32 v9, v41
	v_lshl_add_u64 v[0:1], s[18:19], 0, v[40:41]
	v_lshlrev_b32_e32 v40, 4, v46
	v_addc_co_u32_e32 v3, vcc, 0, v3, vcc
	v_lshl_add_u64 v[10:11], s[18:19], 0, v[8:9]
	s_ashr_i32 s18, s20, 3
	v_lshl_add_u64 v[0:1], v[0:1], 0, v[40:41]
	v_lshl_add_u64 v[12:13], v[10:11], 0, s[12:13]
	v_add_co_u32_e32 v10, vcc, s27, v10
	s_ashr_i32 s17, s16, 31
	s_and_b32 s46, s18, 0xffffffe0
	v_addc_co_u32_e32 v11, vcc, 0, v11, vcc
	flat_load_dwordx4 v[16:19], v[2:3]
	flat_load_dword v44, v[10:11]
	flat_load_dword v47, v[12:13] offset:256
	flat_load_dwordx4 v[20:23], v[0:1]
	s_cmp_eq_u32 s98, 1
	s_cbranch_scc0 .Ls5_nobf0
	global_load_dwordx4 v[116:119], v[0:1], off offset:-1024

; __device__ __forceinline__ void s5_unit(const Args& A, char* lds, int b, int g) {
;     ...
;     for (int i = 0; i < SEQL / 64 + 2; ++i) {
;         if (i < SEQL / 64) { float* BU = (float*)(lds + S5_BU) + (i & 1) * (64 * 132); f32x16 acc = {};
;             acc = __builtin_amdgcn_mfma_f32_32x32x16_bf16(un, bfrag, acc, 0, 0, 0);
;             if (ntile == 0) *(bf16x8*)((bf16*)(lds + S5_US) + ((i & 3) * 64 + ttile * 32 + r32) * 16 + 8 * hi) = un;
;             if (i + 1 < SEQL / 64) un = *(const bf16x8*)(pU + (size_t)(i + 1) * 64 * LD1);
.LBB0_1348:
	s_add_i32 s45, s8, 2
	s_cmp_gt_u32 s45, 31
	s_cbranch_scc1 .LBB0_1353
	s_waitcnt vmcnt(0) lgkmcnt(0)
	s_and_b64 vcc, exec, s[20:21]
	s_cbranch_vccnz .LBB0_1353
	v_mfma_f32_32x32x16_bf16 v[0:15], v[36:39], v[20:23], 0
	s_cmp_eq_u32 s98, 1
	s_cbranch_scc0 .Ls5_noextra_m
	v_mfma_f32_32x32x16_bf16 v[120:135], v[36:39], v[116:119], 0
	s_add_i32 s22, s44, 0x80
	s_and_b32 s22, s22, 0xc0
	v_add_u32_e32 v40, s22, v58
	v_lshl_add_u32 v40, v40, 5, v59
	ds_write_b128 v40, v[36:39]
